# PC scan: three per-chunk scalar loads of lanes 0-31 hoisted before the workgroup barrier (two dependent round trips removed)
# speedup vs baseline: 1.0133x; 1.0013x over previous
.Lscan_nopf:
	s_or_b64 exec, exec, s[14:15]
	v_add_co_u32_e32 v0, vcc, s9, v24
	s_movk_i32 s8, 0x4000
	s_nop 0
	v_addc_co_u32_e32 v1, vcc, 0, v25, vcc
	global_load_dword v41, v[24:25], off
	global_load_dword v42, v[26:27], off
	global_load_dword v43, v[0:1], off
	v_add_co_u32_e32 v0, vcc, s8, v26
	s_mov_b32 s10, 0x20000
	s_nop 0
	v_addc_co_u32_e32 v1, vcc, 0, v27, vcc
	global_load_dword v44, v[0:1], off
	v_add_co_u32_e32 v0, vcc, s10, v24
	s_mov_b32 s8, 0x8000
	s_nop 0
	v_addc_co_u32_e32 v1, vcc, 0, v25, vcc
	global_load_dword v45, v[0:1], off
	v_add_co_u32_e32 v0, vcc, s8, v26
	s_mov_b32 s11, 0x30000
	s_nop 0
	v_addc_co_u32_e32 v1, vcc, 0, v27, vcc
	global_load_dword v46, v[0:1], off
	v_add_co_u32_e32 v0, vcc, s11, v24
	s_mov_b32 s8, 0xc000
	s_nop 0
	v_addc_co_u32_e32 v1, vcc, 0, v25, vcc
	global_load_dword v47, v[0:1], off
	v_add_co_u32_e32 v0, vcc, s8, v26
	s_mov_b32 s8, 0x40000
	s_nop 0
	v_addc_co_u32_e32 v1, vcc, 0, v27, vcc
	global_load_dword v48, v[0:1], off
	v_add_co_u32_e32 v0, vcc, s8, v24
	s_mov_b32 s8, 0x50000
	s_nop 0
	v_addc_co_u32_e32 v1, vcc, 0, v25, vcc
	global_load_dword v49, v[0:1], off
	v_add_co_u32_e32 v0, vcc, s9, v26
	s_nop 1
	v_addc_co_u32_e32 v1, vcc, 0, v27, vcc
	global_load_dword v50, v[0:1], off
	v_add_co_u32_e32 v0, vcc, s8, v24
	s_mov_b32 s8, 0x14000
	s_nop 0
	v_addc_co_u32_e32 v1, vcc, 0, v25, vcc
	global_load_dword v51, v[0:1], off
	v_add_co_u32_e32 v0, vcc, s8, v26
	s_mov_b32 s8, 0x60000
	s_nop 0
	v_addc_co_u32_e32 v1, vcc, 0, v27, vcc
	global_load_dword v52, v[0:1], off
	v_add_co_u32_e32 v0, vcc, s8, v24
	s_mov_b32 s8, 0x18000
	s_nop 0
	v_addc_co_u32_e32 v1, vcc, 0, v25, vcc
	global_load_dword v53, v[0:1], off
	v_add_co_u32_e32 v0, vcc, s8, v26
	s_mov_b32 s8, 0x70000
	s_nop 0
	v_addc_co_u32_e32 v1, vcc, 0, v27, vcc
	global_load_dword v54, v[0:1], off
	v_add_co_u32_e32 v0, vcc, s8, v24
	s_mov_b32 s8, 0x1c000
	s_nop 0
	v_addc_co_u32_e32 v1, vcc, 0, v25, vcc
	global_load_dword v55, v[0:1], off
	v_add_co_u32_e32 v0, vcc, s8, v26
	s_mov_b32 s8, 0x80000
	s_nop 0
	v_addc_co_u32_e32 v1, vcc, 0, v27, vcc
	global_load_dword v56, v[0:1], off
	v_add_co_u32_e32 v0, vcc, s8, v24
	s_mov_b32 s8, 0x90000
	s_nop 0
	v_addc_co_u32_e32 v1, vcc, 0, v25, vcc
	global_load_dword v57, v[0:1], off
	v_add_co_u32_e32 v0, vcc, s10, v26
	s_nop 1
	v_addc_co_u32_e32 v1, vcc, 0, v27, vcc
	global_load_dword v58, v[0:1], off
	v_add_co_u32_e32 v0, vcc, s8, v24
	s_mov_b32 s8, 0x24000
	s_nop 0
	v_addc_co_u32_e32 v1, vcc, 0, v25, vcc
	global_load_dword v59, v[0:1], off
	v_add_co_u32_e32 v0, vcc, s8, v26
	s_mov_b32 s8, 0xa0000
	s_nop 0
	v_addc_co_u32_e32 v1, vcc, 0, v27, vcc
	global_load_dword v60, v[0:1], off
	v_add_co_u32_e32 v0, vcc, s8, v24
	s_mov_b32 s8, 0x28000
	s_nop 0
	v_addc_co_u32_e32 v1, vcc, 0, v25, vcc
	global_load_dword v61, v[0:1], off
	v_add_co_u32_e32 v0, vcc, s8, v26
	s_mov_b32 s8, 0xb0000
	s_nop 0
	v_addc_co_u32_e32 v1, vcc, 0, v27, vcc
	global_load_dword v62, v[0:1], off
	v_add_co_u32_e32 v0, vcc, s8, v24
	s_mov_b32 s8, 0x2c000
	s_nop 0
	v_addc_co_u32_e32 v1, vcc, 0, v25, vcc
	global_load_dword v63, v[0:1], off
	v_add_co_u32_e32 v0, vcc, s8, v26
	s_mov_b32 s8, 0xc0000
	s_nop 0
	v_addc_co_u32_e32 v1, vcc, 0, v27, vcc
	global_load_dword v64, v[0:1], off
	v_add_co_u32_e32 v0, vcc, s8, v24
	s_mov_b32 s8, 0xd0000
	s_nop 0
	v_addc_co_u32_e32 v1, vcc, 0, v25, vcc
	global_load_dword v12, v[0:1], off
	v_add_co_u32_e32 v0, vcc, s11, v26
	s_nop 1
	v_addc_co_u32_e32 v1, vcc, 0, v27, vcc
	global_load_dword v14, v[0:1], off
	v_add_co_u32_e32 v0, vcc, s8, v24
	s_mov_b32 s8, 0x34000
	s_nop 0
	v_addc_co_u32_e32 v1, vcc, 0, v25, vcc
	global_load_dword v13, v[0:1], off
	v_add_co_u32_e32 v0, vcc, s8, v26
	s_mov_b32 s8, 0xe0000
	s_nop 0
	v_addc_co_u32_e32 v1, vcc, 0, v27, vcc
	global_load_dword v15, v[0:1], off
	v_add_co_u32_e32 v0, vcc, s8, v24
	s_mov_b32 s8, 0x38000
	s_nop 0
	v_addc_co_u32_e32 v1, vcc, 0, v25, vcc
	global_load_dword v16, v[0:1], off
	v_add_co_u32_e32 v0, vcc, s8, v26
	s_nop 1
	v_addc_co_u32_e32 v1, vcc, 0, v27, vcc
	global_load_dword v18, v[0:1], off
	v_add_co_u32_e32 v0, vcc, 0xf0000, v24
	s_nop 1
	v_addc_co_u32_e32 v1, vcc, 0, v25, vcc
	global_load_dword v17, v[0:1], off
	v_add_co_u32_e32 v0, vcc, 0x3c000, v26
	s_nop 1
	v_addc_co_u32_e32 v1, vcc, 0, v27, vcc
	global_load_dword v19, v[0:1], off
	s_and_saveexec_b64 s[8:9], s[38:39]
	s_cbranch_execz .Lpc_h_skip
	v_lshlrev_b32_e32 v146, 5, v28
	v_add_u32_e32 v148, v36, v146
	v_ashrrev_i32_e32 v149, 31, v148
	v_lshl_add_u64 v[148:149], v[148:149], 2, s[70:71]
	global_load_dword v150, v[148:149], off
	v_add_u32_e32 v148, v38, v146
	v_ashrrev_i32_e32 v149, 31, v148
	v_lshl_add_u64 v[148:149], v[148:149], 2, s[70:71]
	global_load_dword v151, v[148:149], off
	v_lshl_add_u32 v148, v30, 5, v39
	v_ashrrev_i32_e32 v149, 31, v148
	v_lshl_add_u64 v[148:149], v[148:149], 2, s[70:71]
	global_load_dword v152, v[148:149], off
.Lpc_h_skip:
	s_mov_b64 exec, s[8:9]
	s_waitcnt vmcnt(0)
	s_barrier
	s_and_saveexec_b64 s[8:9], s[38:39]
	s_cbranch_execz .LBB0_146
	ds_write_b32 v37, v151 offset:512
	v_mul_f32_e32 v0, 0x3fb8aa3b, v152
	v_exp_f32_e32 v0, v0
	ds_write2_b32 v37, v0, v150 offset0:64 offset1:96
